# GEMM tile loop: second accumulator clear removed (mlp1/uq/ukv); mlp1 epilogue relu^2 as max(x,0) squared in place instead of x*x + compare/select per value
# speedup vs baseline: 1.0536x; 1.0022x over previous
;     DI void operator()(const Acc& acc, const Unit& u, int wr, int wc, int fr, int fq) const {
;     ...
; #pragma unroll
;         for (int ai = 0; ai < 2; ++ai)
; #pragma unroll
;             for (int m = 0; m < 4; ++m) {
;                 bf16_t* rp = U + (size_t)(row0 + ai * HALF + m * 16) * 4096 + col0;
; #pragma unroll
;                 for (int bj = 0; bj < 2; ++bj) {
;                     f32x4 a = acc[ai][bj][m][0], b = acc[ai][bj][m][1];
; #pragma unroll
;                     for (int j = 0; j < 4; ++j) { a[j] = a[j] > 0.f ? a[j] * a[j] : 0.f; b[j] = b[j] > 0.f ? b[j] * b[j] : 0.f; }
;                     u32x4 o; o[0] = pk_bf16(a[0], a[1]); o[1] = pk_bf16(a[2], a[3]); o[2] = pk_bf16(b[0], b[1]); o[3] = pk_bf16(b[2], b[3]);
;                     *(u32x4*)(rp + bj * 32) = o;
;                 }
.LBB0_155:
	v_lshl_add_u32 v136, s66, 8, v140
	v_ashrrev_i32_e32 v137, 31, v136
	v_lshl_or_b32 v134, s67, 8, v142
	v_lshlrev_b64 v[138:139], 13, v[136:137]
	v_readlane_b32 s36, v254, 27
	v_ashrrev_i32_e32 v135, 31, v134
	v_readlane_b32 s37, v254, 28
	v_lshl_add_u64 v[144:145], s[36:37], 0, v[138:139]
	v_lshlrev_b64 v[138:139], 1, v[134:135]
	v_lshl_add_u64 v[134:135], v[144:145], 0, v[138:139]
	s_mov_b64 s[54:55], 0x100000
	s_mov_b32 s67, s64
	s_mov_b32 s66, s65
	s_mov_b64 s[56:57], s[52:53]
	v_max_f32_e32 v120, 0, v120
	v_max_f32_e32 v121, 0, v121
	v_max_f32_e32 v122, 0, v122
	v_max_f32_e32 v123, 0, v123
	v_max_f32_e32 v124, 0, v124
	v_max_f32_e32 v125, 0, v125
	v_max_f32_e32 v126, 0, v126
	v_max_f32_e32 v127, 0, v127
	v_pk_mul_f32 v[120:121], v[120:121], v[120:121]
	v_pk_mul_f32 v[122:123], v[122:123], v[122:123]
	v_pk_mul_f32 v[124:125], v[124:125], v[124:125]
	v_pk_mul_f32 v[126:127], v[126:127], v[126:127]
	v_cvt_pk_bf16_f32 v123, v122, v123
	v_cvt_pk_bf16_f32 v122, v120, v121
	v_cvt_pk_bf16_f32 v121, v126, v127
	v_cvt_pk_bf16_f32 v120, v124, v125
	global_store_dwordx4 v[134:135], v[120:123], off
	s_nop 1
	v_max_f32_e32 v112, 0, v112
	v_max_f32_e32 v113, 0, v113
	v_max_f32_e32 v114, 0, v114
	v_max_f32_e32 v115, 0, v115
	v_max_f32_e32 v116, 0, v116
	v_max_f32_e32 v117, 0, v117
	v_max_f32_e32 v118, 0, v118
	v_max_f32_e32 v119, 0, v119
	v_pk_mul_f32 v[112:113], v[112:113], v[112:113]
	v_pk_mul_f32 v[114:115], v[114:115], v[114:115]
	v_pk_mul_f32 v[116:117], v[116:117], v[116:117]
	v_pk_mul_f32 v[118:119], v[118:119], v[118:119]
	v_cvt_pk_bf16_f32 v115, v114, v115
	v_cvt_pk_bf16_f32 v114, v112, v113
	v_cvt_pk_bf16_f32 v113, v118, v119
	v_cvt_pk_bf16_f32 v112, v116, v117
	global_store_dwordx4 v[134:135], v[112:115], off offset:64
	s_nop 1
	v_or_b32_e32 v112, 16, v136
	v_ashrrev_i32_e32 v113, 31, v112
	v_lshlrev_b64 v[112:113], 13, v[112:113]
	v_lshl_add_u64 v[112:113], s[36:37], 0, v[112:113]
	v_lshl_add_u64 v[112:113], v[112:113], 0, v[138:139]
	v_max_f32_e32 v104, 0, v104
	v_max_f32_e32 v105, 0, v105
	v_max_f32_e32 v106, 0, v106
	v_max_f32_e32 v107, 0, v107
	v_max_f32_e32 v108, 0, v108
	v_max_f32_e32 v109, 0, v109
	v_max_f32_e32 v110, 0, v110
	v_max_f32_e32 v111, 0, v111
	v_pk_mul_f32 v[104:105], v[104:105], v[104:105]
	v_pk_mul_f32 v[106:107], v[106:107], v[106:107]
	v_pk_mul_f32 v[108:109], v[108:109], v[108:109]
	v_pk_mul_f32 v[110:111], v[110:111], v[110:111]
	v_cvt_pk_bf16_f32 v107, v106, v107
	v_cvt_pk_bf16_f32 v106, v104, v105
	v_cvt_pk_bf16_f32 v105, v110, v111
	v_cvt_pk_bf16_f32 v104, v108, v109
	global_store_dwordx4 v[112:113], v[104:107], off
	s_nop 1
	v_max_f32_e32 v96, 0, v96
	v_max_f32_e32 v97, 0, v97
	v_max_f32_e32 v98, 0, v98
	v_max_f32_e32 v99, 0, v99
	v_max_f32_e32 v100, 0, v100
	v_max_f32_e32 v101, 0, v101
	v_max_f32_e32 v102, 0, v102
	v_max_f32_e32 v103, 0, v103
	v_pk_mul_f32 v[96:97], v[96:97], v[96:97]
	v_pk_mul_f32 v[98:99], v[98:99], v[98:99]
	v_pk_mul_f32 v[100:101], v[100:101], v[100:101]
	v_pk_mul_f32 v[102:103], v[102:103], v[102:103]
	v_cvt_pk_bf16_f32 v99, v98, v99
	v_cvt_pk_bf16_f32 v98, v96, v97
	v_cvt_pk_bf16_f32 v97, v102, v103
	v_cvt_pk_bf16_f32 v96, v100, v101
	global_store_dwordx4 v[112:113], v[96:99], off offset:64
	s_nop 1
	v_or_b32_e32 v96, 32, v136
	v_ashrrev_i32_e32 v97, 31, v96
	v_lshlrev_b64 v[96:97], 13, v[96:97]
	v_lshl_add_u64 v[96:97], s[36:37], 0, v[96:97]
	v_lshl_add_u64 v[96:97], v[96:97], 0, v[138:139]
	v_max_f32_e32 v88, 0, v88
	v_max_f32_e32 v89, 0, v89
	v_max_f32_e32 v90, 0, v90
	v_max_f32_e32 v91, 0, v91
	v_max_f32_e32 v92, 0, v92
	v_max_f32_e32 v93, 0, v93
	v_max_f32_e32 v94, 0, v94
	v_max_f32_e32 v95, 0, v95
	v_pk_mul_f32 v[88:89], v[88:89], v[88:89]
	v_pk_mul_f32 v[90:91], v[90:91], v[90:91]
	v_pk_mul_f32 v[92:93], v[92:93], v[92:93]
	v_pk_mul_f32 v[94:95], v[94:95], v[94:95]
	v_cvt_pk_bf16_f32 v91, v90, v91
	v_cvt_pk_bf16_f32 v90, v88, v89
	v_cvt_pk_bf16_f32 v89, v94, v95
	v_cvt_pk_bf16_f32 v88, v92, v93
	global_store_dwordx4 v[96:97], v[88:91], off
	s_nop 1
	v_max_f32_e32 v80, 0, v80
	v_max_f32_e32 v81, 0, v81
	v_max_f32_e32 v82, 0, v82
	v_max_f32_e32 v83, 0, v83
	v_max_f32_e32 v84, 0, v84
	v_max_f32_e32 v85, 0, v85
	v_max_f32_e32 v86, 0, v86
	v_max_f32_e32 v87, 0, v87
	v_pk_mul_f32 v[80:81], v[80:81], v[80:81]
	v_pk_mul_f32 v[82:83], v[82:83], v[82:83]
	v_pk_mul_f32 v[84:85], v[84:85], v[84:85]
	v_pk_mul_f32 v[86:87], v[86:87], v[86:87]
	v_cvt_pk_bf16_f32 v83, v82, v83
	v_cvt_pk_bf16_f32 v82, v80, v81
	v_cvt_pk_bf16_f32 v81, v86, v87
	v_cvt_pk_bf16_f32 v80, v84, v85
	global_store_dwordx4 v[96:97], v[80:83], off offset:64
	s_nop 1
	v_or_b32_e32 v80, 48, v136
	v_ashrrev_i32_e32 v81, 31, v80
	v_lshlrev_b64 v[80:81], 13, v[80:81]
	v_lshl_add_u64 v[80:81], s[36:37], 0, v[80:81]
	v_lshl_add_u64 v[80:81], v[80:81], 0, v[138:139]
	v_max_f32_e32 v72, 0, v72
	v_max_f32_e32 v73, 0, v73
	v_max_f32_e32 v74, 0, v74
	v_max_f32_e32 v75, 0, v75
	v_max_f32_e32 v76, 0, v76
	v_max_f32_e32 v77, 0, v77
	v_max_f32_e32 v78, 0, v78
	v_max_f32_e32 v79, 0, v79
	v_pk_mul_f32 v[72:73], v[72:73], v[72:73]
	v_pk_mul_f32 v[74:75], v[74:75], v[74:75]
	v_pk_mul_f32 v[76:77], v[76:77], v[76:77]
	v_pk_mul_f32 v[78:79], v[78:79], v[78:79]
	v_cvt_pk_bf16_f32 v75, v74, v75
	v_cvt_pk_bf16_f32 v74, v72, v73
	v_cvt_pk_bf16_f32 v73, v78, v79
	v_cvt_pk_bf16_f32 v72, v76, v77
	global_store_dwordx4 v[80:81], v[72:75], off
	s_nop 1
	v_max_f32_e32 v64, 0, v64
	v_max_f32_e32 v65, 0, v65
	v_max_f32_e32 v66, 0, v66
	v_max_f32_e32 v67, 0, v67
	v_max_f32_e32 v68, 0, v68
	v_max_f32_e32 v69, 0, v69
	v_max_f32_e32 v70, 0, v70
	v_max_f32_e32 v71, 0, v71
	v_pk_mul_f32 v[64:65], v[64:65], v[64:65]
	v_pk_mul_f32 v[66:67], v[66:67], v[66:67]
;     DI void operator()(const Acc& acc, const Unit& u, int wr, int wc, int fr, int fq) const {
;     ...
; #pragma unroll
;         for (int ai = 0; ai < 2; ++ai)
; #pragma unroll
;             for (int m = 0; m < 4; ++m) {
;                 bf16_t* rp = U + (size_t)(row0 + ai * HALF + m * 16) * 4096 + col0;
; #pragma unroll
;                 for (int bj = 0; bj < 2; ++bj) {
;                     f32x4 a = acc[ai][bj][m][0], b = acc[ai][bj][m][1];
; #pragma unroll
;                     for (int j = 0; j < 4; ++j) { a[j] = a[j] > 0.f ? a[j] * a[j] : 0.f; b[j] = b[j] > 0.f ? b[j] * b[j] : 0.f; }
;                     u32x4 o; o[0] = pk_bf16(a[0], a[1]); o[1] = pk_bf16(a[2], a[3]); o[2] = pk_bf16(b[0], b[1]); o[3] = pk_bf16(b[2], b[3]);
;                     *(u32x4*)(rp + bj * 32) = o;
;                 }
	v_pk_mul_f32 v[68:69], v[68:69], v[68:69]
	v_pk_mul_f32 v[70:71], v[70:71], v[70:71]
	v_cvt_pk_bf16_f32 v67, v66, v67
	v_cvt_pk_bf16_f32 v66, v64, v65
	v_cvt_pk_bf16_f32 v65, v70, v71
	v_cvt_pk_bf16_f32 v64, v68, v69
	global_store_dwordx4 v[80:81], v[64:67], off offset:64
	s_nop 1
	v_lshl_add_u64 v[64:65], v[134:135], 0, s[54:55]
	s_mov_b32 s54, 0x100000
	v_max_f32_e32 v56, 0, v56
	v_max_f32_e32 v57, 0, v57
	v_max_f32_e32 v58, 0, v58
	v_max_f32_e32 v59, 0, v59
	v_max_f32_e32 v60, 0, v60
	v_max_f32_e32 v61, 0, v61
	v_max_f32_e32 v62, 0, v62
	v_max_f32_e32 v63, 0, v63
	v_pk_mul_f32 v[56:57], v[56:57], v[56:57]
	v_pk_mul_f32 v[58:59], v[58:59], v[58:59]
	v_pk_mul_f32 v[60:61], v[60:61], v[60:61]
	v_pk_mul_f32 v[62:63], v[62:63], v[62:63]
	v_cvt_pk_bf16_f32 v59, v58, v59
	v_cvt_pk_bf16_f32 v58, v56, v57
	v_cvt_pk_bf16_f32 v57, v62, v63
	v_cvt_pk_bf16_f32 v56, v60, v61
	v_add_co_u32_e32 v60, vcc, s54, v134
	s_mov_b64 s[54:55], 0x120000
	s_nop 0
	v_addc_co_u32_e32 v61, vcc, 0, v135, vcc
	global_store_dwordx4 v[60:61], v[56:59], off
	s_nop 1
	v_max_f32_e32 v48, 0, v48
	v_max_f32_e32 v49, 0, v49
	v_max_f32_e32 v50, 0, v50
	v_max_f32_e32 v51, 0, v51
	v_max_f32_e32 v52, 0, v52
	v_max_f32_e32 v53, 0, v53
	v_max_f32_e32 v54, 0, v54
	v_max_f32_e32 v55, 0, v55
	v_pk_mul_f32 v[48:49], v[48:49], v[48:49]
	v_pk_mul_f32 v[50:51], v[50:51], v[50:51]
	v_pk_mul_f32 v[52:53], v[52:53], v[52:53]
	v_pk_mul_f32 v[54:55], v[54:55], v[54:55]
	v_cvt_pk_bf16_f32 v51, v50, v51
	v_cvt_pk_bf16_f32 v50, v48, v49
	v_cvt_pk_bf16_f32 v49, v54, v55
	v_cvt_pk_bf16_f32 v48, v52, v53
	global_store_dwordx4 v[64:65], v[48:51], off offset:64
	s_nop 1
	v_lshl_add_u64 v[48:49], v[134:135], 0, s[54:55]
	s_mov_b32 s54, 0x120000
	v_max_f32_e32 v40, 0, v40
	v_max_f32_e32 v41, 0, v41
	v_max_f32_e32 v42, 0, v42
	v_max_f32_e32 v43, 0, v43
	v_max_f32_e32 v44, 0, v44
	v_max_f32_e32 v45, 0, v45
	v_max_f32_e32 v46, 0, v46
	v_max_f32_e32 v47, 0, v47
	v_pk_mul_f32 v[40:41], v[40:41], v[40:41]
	v_pk_mul_f32 v[42:43], v[42:43], v[42:43]
	v_pk_mul_f32 v[44:45], v[44:45], v[44:45]
	v_pk_mul_f32 v[46:47], v[46:47], v[46:47]
	v_cvt_pk_bf16_f32 v43, v42, v43
	v_cvt_pk_bf16_f32 v42, v40, v41
	v_cvt_pk_bf16_f32 v41, v46, v47
	v_cvt_pk_bf16_f32 v40, v44, v45
	v_add_co_u32_e32 v44, vcc, s54, v134
	s_mov_b64 s[54:55], 0x140000
	s_nop 0
	v_addc_co_u32_e32 v45, vcc, 0, v135, vcc
	global_store_dwordx4 v[44:45], v[40:43], off
	s_nop 1
	v_max_f32_e32 v32, 0, v32
	v_max_f32_e32 v33, 0, v33
	v_max_f32_e32 v34, 0, v34
	v_max_f32_e32 v35, 0, v35
	v_max_f32_e32 v36, 0, v36
	v_max_f32_e32 v37, 0, v37
	v_max_f32_e32 v38, 0, v38
	v_max_f32_e32 v39, 0, v39
	v_pk_mul_f32 v[32:33], v[32:33], v[32:33]
	v_pk_mul_f32 v[34:35], v[34:35], v[34:35]
	v_pk_mul_f32 v[36:37], v[36:37], v[36:37]
	v_pk_mul_f32 v[38:39], v[38:39], v[38:39]
	v_cvt_pk_bf16_f32 v35, v34, v35
	v_cvt_pk_bf16_f32 v34, v32, v33
	v_cvt_pk_bf16_f32 v33, v38, v39
	v_cvt_pk_bf16_f32 v32, v36, v37
	global_store_dwordx4 v[48:49], v[32:35], off offset:64
	s_nop 1
	v_lshl_add_u64 v[32:33], v[134:135], 0, s[54:55]
	s_mov_b32 s54, 0x140000
	v_max_f32_e32 v24, 0, v24
	v_max_f32_e32 v25, 0, v25
	v_max_f32_e32 v26, 0, v26
	v_max_f32_e32 v27, 0, v27
	v_max_f32_e32 v28, 0, v28
	v_max_f32_e32 v29, 0, v29
	v_max_f32_e32 v30, 0, v30
	v_max_f32_e32 v31, 0, v31
	v_pk_mul_f32 v[24:25], v[24:25], v[24:25]
	v_pk_mul_f32 v[26:27], v[26:27], v[26:27]
	v_pk_mul_f32 v[28:29], v[28:29], v[28:29]
	v_pk_mul_f32 v[30:31], v[30:31], v[30:31]
	v_cvt_pk_bf16_f32 v27, v26, v27
	v_cvt_pk_bf16_f32 v26, v24, v25
	v_cvt_pk_bf16_f32 v25, v30, v31
	v_cvt_pk_bf16_f32 v24, v28, v29
	v_add_co_u32_e32 v28, vcc, s54, v134
	s_mov_b64 s[54:55], 0x160000
	s_nop 0
	v_addc_co_u32_e32 v29, vcc, 0, v135, vcc
	global_store_dwordx4 v[28:29], v[24:27], off
	s_nop 1
	v_max_f32_e32 v16, 0, v16
	v_max_f32_e32 v17, 0, v17
	v_max_f32_e32 v18, 0, v18
	v_max_f32_e32 v19, 0, v19
	v_max_f32_e32 v20, 0, v20
	v_max_f32_e32 v21, 0, v21
	v_max_f32_e32 v22, 0, v22
	v_max_f32_e32 v23, 0, v23
	v_pk_mul_f32 v[16:17], v[16:17], v[16:17]
	v_pk_mul_f32 v[18:19], v[18:19], v[18:19]
	v_pk_mul_f32 v[20:21], v[20:21], v[20:21]
	v_pk_mul_f32 v[22:23], v[22:23], v[22:23]
	v_cvt_pk_bf16_f32 v19, v18, v19
	v_cvt_pk_bf16_f32 v18, v16, v17
	v_cvt_pk_bf16_f32 v17, v22, v23
	v_cvt_pk_bf16_f32 v16, v20, v21
	global_store_dwordx4 v[32:33], v[16:19], off offset:64
	s_nop 1
	v_lshl_add_u64 v[16:17], v[134:135], 0, s[54:55]
	s_mov_b32 s54, 0x160000
	v_max_f32_e32 v8, 0, v8
	v_max_f32_e32 v9, 0, v9
	v_max_f32_e32 v10, 0, v10
	v_max_f32_e32 v11, 0, v11
	v_max_f32_e32 v12, 0, v12
	v_max_f32_e32 v13, 0, v13
	v_max_f32_e32 v14, 0, v14
	v_max_f32_e32 v15, 0, v15
	v_pk_mul_f32 v[8:9], v[8:9], v[8:9]
	v_pk_mul_f32 v[10:11], v[10:11], v[10:11]
	v_pk_mul_f32 v[12:13], v[12:13], v[12:13]
	v_pk_mul_f32 v[14:15], v[14:15], v[14:15]
	v_cvt_pk_bf16_f32 v11, v10, v11
	v_cvt_pk_bf16_f32 v10, v8, v9
	v_cvt_pk_bf16_f32 v9, v14, v15
	v_cvt_pk_bf16_f32 v8, v12, v13
	v_add_co_u32_e32 v12, vcc, s54, v134
	s_mov_b64 s[54:55], s[12:13]
	s_nop 0
	v_addc_co_u32_e32 v13, vcc, 0, v135, vcc
	global_store_dwordx4 v[12:13], v[8:11], off
	s_nop 1
	s_and_b64 vcc, exec, s[10:11]
	v_max_f32_e32 v0, 0, v0
	v_max_f32_e32 v1, 0, v1
	v_max_f32_e32 v2, 0, v2
	v_max_f32_e32 v3, 0, v3
	v_max_f32_e32 v4, 0, v4
	v_max_f32_e32 v5, 0, v5
	v_max_f32_e32 v6, 0, v6
	v_max_f32_e32 v7, 0, v7
	v_pk_mul_f32 v[0:1], v[0:1], v[0:1]
	v_pk_mul_f32 v[2:3], v[2:3], v[2:3]
	v_pk_mul_f32 v[4:5], v[4:5], v[4:5]
	v_pk_mul_f32 v[6:7], v[6:7], v[6:7]
	v_cvt_pk_bf16_f32 v3, v2, v3
	v_cvt_pk_bf16_f32 v2, v0, v1
	v_cvt_pk_bf16_f32 v1, v6, v7
	v_cvt_pk_bf16_f32 v0, v4, v5
	global_store_dwordx4 v[16:17], v[0:3], off offset:64
	s_nop 1
	s_cbranch_vccnz .LBB0_169

; template <class Epi>
; DI void gemm_phase(const int TID, const int BID, LAS unsigned char* lds, const Gemm g, const Epi& E) {
;     ...
;         for (int a = 0; a < 2; ++a)
; #pragma unroll
;             for (int b = 0; b < 2; ++b)
; #pragma unroll
;                 for (int m = 0; m < 4; ++m)
; #pragma unroll
;                     for (int n = 0; n < 2; ++n) acc[a][b][m][n] = (f32x4){0.f, 0.f, 0.f, 0.f};
;         cur = nxt; cA = nA; cB = nB; ++ui;
.LBB0_162:
	v_mov_b32_e32 v127, 0
	s_andn2_b64 vcc, exec, s[8:9]
	v_mov_b32_e32 v126, v127
	v_mov_b32_e32 v125, v127
	v_mov_b32_e32 v124, v127
	v_mov_b32_e32 v123, v127
	v_mov_b32_e32 v122, v127
	v_mov_b32_e32 v121, v127
	v_mov_b32_e32 v120, v127
	v_mov_b32_e32 v111, v127
	v_mov_b32_e32 v110, v127
	v_mov_b32_e32 v109, v127
	v_mov_b32_e32 v108, v127
	v_mov_b32_e32 v107, v127
	v_mov_b32_e32 v106, v127
	v_mov_b32_e32 v105, v127
	v_mov_b32_e32 v104, v127
	v_mov_b32_e32 v95, v127
	v_mov_b32_e32 v94, v127
	v_mov_b32_e32 v93, v127
	v_mov_b32_e32 v92, v127
	v_mov_b32_e32 v91, v127
	v_mov_b32_e32 v90, v127
	v_mov_b32_e32 v89, v127
	v_mov_b32_e32 v88, v127
	v_mov_b32_e32 v79, v127
	v_mov_b32_e32 v78, v127
	v_mov_b32_e32 v77, v127
	v_mov_b32_e32 v76, v127
	v_mov_b32_e32 v75, v127
	v_mov_b32_e32 v74, v127
	v_mov_b32_e32 v73, v127
	v_mov_b32_e32 v72, v127
	v_mov_b32_e32 v119, v127
	v_mov_b32_e32 v118, v127
	v_mov_b32_e32 v117, v127
	v_mov_b32_e32 v116, v127
	v_mov_b32_e32 v115, v127
	v_mov_b32_e32 v114, v127
	v_mov_b32_e32 v113, v127
	v_mov_b32_e32 v112, v127
	v_mov_b32_e32 v103, v127
	v_mov_b32_e32 v102, v127
	v_mov_b32_e32 v101, v127
	v_mov_b32_e32 v100, v127
	v_mov_b32_e32 v99, v127
	v_mov_b32_e32 v98, v127
	v_mov_b32_e32 v97, v127
	v_mov_b32_e32 v96, v127
	v_mov_b32_e32 v87, v127
	v_mov_b32_e32 v86, v127
	v_mov_b32_e32 v85, v127
	v_mov_b32_e32 v84, v127
	v_mov_b32_e32 v83, v127
	v_mov_b32_e32 v82, v127
	v_mov_b32_e32 v81, v127
	v_mov_b32_e32 v80, v127
	v_mov_b32_e32 v71, v127
	v_mov_b32_e32 v70, v127
	v_mov_b32_e32 v69, v127
	v_mov_b32_e32 v68, v127
	v_mov_b32_e32 v67, v127
	v_mov_b32_e32 v66, v127
	v_mov_b32_e32 v65, v127
	v_mov_b32_e32 v64, v127
	v_mov_b32_e32 v63, v127
	v_mov_b32_e32 v62, v127
	v_mov_b32_e32 v61, v127
	v_mov_b32_e32 v60, v127
	v_mov_b32_e32 v59, v127
	v_mov_b32_e32 v58, v127
	v_mov_b32_e32 v57, v127
	v_mov_b32_e32 v56, v127
	v_mov_b32_e32 v47, v127
	v_mov_b32_e32 v46, v127
	v_mov_b32_e32 v45, v127
	v_mov_b32_e32 v44, v127
	v_mov_b32_e32 v43, v127
	v_mov_b32_e32 v42, v127
	v_mov_b32_e32 v41, v127
	v_mov_b32_e32 v40, v127
	v_mov_b32_e32 v31, v127
	v_mov_b32_e32 v30, v127
	v_mov_b32_e32 v29, v127
	v_mov_b32_e32 v28, v127
	v_mov_b32_e32 v27, v127
	v_mov_b32_e32 v26, v127
	v_mov_b32_e32 v25, v127
	v_mov_b32_e32 v24, v127
	v_mov_b32_e32 v15, v127
	v_mov_b32_e32 v14, v127
	v_mov_b32_e32 v13, v127
	v_mov_b32_e32 v12, v127
	v_mov_b32_e32 v11, v127
	v_mov_b32_e32 v10, v127
	v_mov_b32_e32 v9, v127
	v_mov_b32_e32 v8, v127
	v_mov_b32_e32 v55, v127
	v_mov_b32_e32 v54, v127
	v_mov_b32_e32 v53, v127
	v_mov_b32_e32 v52, v127
	v_mov_b32_e32 v51, v127
	v_mov_b32_e32 v50, v127
	v_mov_b32_e32 v49, v127
	v_mov_b32_e32 v48, v127
	v_mov_b32_e32 v39, v127
	v_mov_b32_e32 v38, v127
	v_mov_b32_e32 v37, v127
	v_mov_b32_e32 v36, v127
	v_mov_b32_e32 v35, v127
	v_mov_b32_e32 v34, v127
	v_mov_b32_e32 v33, v127
	v_mov_b32_e32 v32, v127
	v_mov_b32_e32 v23, v127
	v_mov_b32_e32 v22, v127
	v_mov_b32_e32 v21, v127
	v_mov_b32_e32 v20, v127
	v_mov_b32_e32 v19, v127
	v_mov_b32_e32 v18, v127
	v_mov_b32_e32 v17, v127
	v_mov_b32_e32 v16, v127
	v_mov_b32_e32 v7, v127
	v_mov_b32_e32 v6, v127
	v_mov_b32_e32 v5, v127
	v_mov_b32_e32 v4, v127
	v_mov_b32_e32 v3, v127
	v_mov_b32_e32 v2, v127
	v_mov_b32_e32 v1, v127
	v_mov_b32_e32 v0, v127
	s_cbranch_vccnz .LBB0_155
	s_add_u32 s54, s54, 0x80
	s_addc_u32 s55, s55, 0
	s_add_u32 s76, s56, 0x100
	s_addc_u32 s77, s57, 0
	s_mov_b32 s56, 0

; template <class Epi>
; DI void gemm_phase(const int TID, const int BID, LAS unsigned char* lds, const Gemm g, const Epi& E) {
;     ...
;         for (int a = 0; a < 2; ++a)
; #pragma unroll
;             for (int b = 0; b < 2; ++b)
; #pragma unroll
;                 for (int m = 0; m < 4; ++m)
; #pragma unroll
;                     for (int n = 0; n < 2; ++n) acc[a][b][m][n] = (f32x4){0.f, 0.f, 0.f, 0.f};
;         cur = nxt; cA = nA; cB = nB; ++ui;
.LBB0_357:
	v_mov_b32_e32 v127, 0
	s_andn2_b64 vcc, exec, s[48:49]
	v_mov_b32_e32 v126, v127
	v_mov_b32_e32 v125, v127
	v_mov_b32_e32 v124, v127
	v_mov_b32_e32 v123, v127
	v_mov_b32_e32 v122, v127
	v_mov_b32_e32 v121, v127
	v_mov_b32_e32 v120, v127
	v_mov_b32_e32 v111, v127
	v_mov_b32_e32 v110, v127
	v_mov_b32_e32 v109, v127
	v_mov_b32_e32 v108, v127
	v_mov_b32_e32 v107, v127
	v_mov_b32_e32 v106, v127
	v_mov_b32_e32 v105, v127
	v_mov_b32_e32 v104, v127
	v_mov_b32_e32 v95, v127
	v_mov_b32_e32 v94, v127
	v_mov_b32_e32 v93, v127
	v_mov_b32_e32 v92, v127
	v_mov_b32_e32 v91, v127
	v_mov_b32_e32 v90, v127
	v_mov_b32_e32 v89, v127
	v_mov_b32_e32 v88, v127
	v_mov_b32_e32 v79, v127
	v_mov_b32_e32 v78, v127
	v_mov_b32_e32 v77, v127
	v_mov_b32_e32 v76, v127
	v_mov_b32_e32 v75, v127
	v_mov_b32_e32 v74, v127
	v_mov_b32_e32 v73, v127
	v_mov_b32_e32 v72, v127
	v_mov_b32_e32 v119, v127
	v_mov_b32_e32 v118, v127
	v_mov_b32_e32 v117, v127
	v_mov_b32_e32 v116, v127
	v_mov_b32_e32 v115, v127
	v_mov_b32_e32 v114, v127
	v_mov_b32_e32 v113, v127
	v_mov_b32_e32 v112, v127
	v_mov_b32_e32 v103, v127
	v_mov_b32_e32 v102, v127
	v_mov_b32_e32 v101, v127
	v_mov_b32_e32 v100, v127
	v_mov_b32_e32 v99, v127
	v_mov_b32_e32 v98, v127
	v_mov_b32_e32 v97, v127
	v_mov_b32_e32 v96, v127
	v_mov_b32_e32 v87, v127
	v_mov_b32_e32 v86, v127
	v_mov_b32_e32 v85, v127
	v_mov_b32_e32 v84, v127
	v_mov_b32_e32 v83, v127
	v_mov_b32_e32 v82, v127
	v_mov_b32_e32 v81, v127
	v_mov_b32_e32 v80, v127
	v_mov_b32_e32 v71, v127
	v_mov_b32_e32 v70, v127
	v_mov_b32_e32 v69, v127
	v_mov_b32_e32 v68, v127
	v_mov_b32_e32 v67, v127
	v_mov_b32_e32 v66, v127
	v_mov_b32_e32 v65, v127
	v_mov_b32_e32 v64, v127
	v_mov_b32_e32 v63, v127
	v_mov_b32_e32 v62, v127
	v_mov_b32_e32 v61, v127
	v_mov_b32_e32 v60, v127
	v_mov_b32_e32 v59, v127
	v_mov_b32_e32 v58, v127
	v_mov_b32_e32 v57, v127
	v_mov_b32_e32 v56, v127
	v_mov_b32_e32 v47, v127
	v_mov_b32_e32 v46, v127
	v_mov_b32_e32 v45, v127
	v_mov_b32_e32 v44, v127
	v_mov_b32_e32 v43, v127
	v_mov_b32_e32 v42, v127
	v_mov_b32_e32 v41, v127
	v_mov_b32_e32 v40, v127
	v_mov_b32_e32 v31, v127
	v_mov_b32_e32 v30, v127
	v_mov_b32_e32 v29, v127
	v_mov_b32_e32 v28, v127
	v_mov_b32_e32 v27, v127
	v_mov_b32_e32 v26, v127
	v_mov_b32_e32 v25, v127
	v_mov_b32_e32 v24, v127
	v_mov_b32_e32 v15, v127
	v_mov_b32_e32 v14, v127
	v_mov_b32_e32 v13, v127
	v_mov_b32_e32 v12, v127
	v_mov_b32_e32 v11, v127
	v_mov_b32_e32 v10, v127
	v_mov_b32_e32 v9, v127
	v_mov_b32_e32 v8, v127
	v_mov_b32_e32 v55, v127
	v_mov_b32_e32 v54, v127
	v_mov_b32_e32 v53, v127
	v_mov_b32_e32 v52, v127
	v_mov_b32_e32 v51, v127
	v_mov_b32_e32 v50, v127
	v_mov_b32_e32 v49, v127
	v_mov_b32_e32 v48, v127
	v_mov_b32_e32 v39, v127
	v_mov_b32_e32 v38, v127
	v_mov_b32_e32 v37, v127
	v_mov_b32_e32 v36, v127
	v_mov_b32_e32 v35, v127
	v_mov_b32_e32 v34, v127
	v_mov_b32_e32 v33, v127
	v_mov_b32_e32 v32, v127
	v_mov_b32_e32 v23, v127
	v_mov_b32_e32 v22, v127
	v_mov_b32_e32 v21, v127
	v_mov_b32_e32 v20, v127
	v_mov_b32_e32 v19, v127
	v_mov_b32_e32 v18, v127
	v_mov_b32_e32 v17, v127
	v_mov_b32_e32 v16, v127
	v_mov_b32_e32 v7, v127
	v_mov_b32_e32 v6, v127
	v_mov_b32_e32 v5, v127
	v_mov_b32_e32 v4, v127
	v_mov_b32_e32 v3, v127
	v_mov_b32_e32 v2, v127
	v_mov_b32_e32 v1, v127
	v_mov_b32_e32 v0, v127
	s_cbranch_vccnz .LBB0_360
	s_add_u32 s6, s6, 0x80
	s_addc_u32 s7, s7, 0
	s_add_u32 s12, s8, 0x100
	s_addc_u32 s13, s9, 0
	s_mov_b32 s8, 0

; template <class Epi>
; DI void gemm_phase(const int TID, const int BID, LAS unsigned char* lds, const Gemm g, const Epi& E) {
;     ...
;         for (int a = 0; a < 2; ++a)
; #pragma unroll
;             for (int b = 0; b < 2; ++b)
; #pragma unroll
;                 for (int m = 0; m < 4; ++m)
; #pragma unroll
;                     for (int n = 0; n < 2; ++n) acc[a][b][m][n] = (f32x4){0.f, 0.f, 0.f, 0.f};
;         cur = nxt; cA = nA; cB = nB; ++ui;
.LBB0_489:
	v_mov_b32_e32 v127, 0
	s_andn2_b64 vcc, exec, s[10:11]
	v_mov_b32_e32 v126, v127
	v_mov_b32_e32 v125, v127
	v_mov_b32_e32 v124, v127
	v_mov_b32_e32 v123, v127
	v_mov_b32_e32 v122, v127
	v_mov_b32_e32 v121, v127
	v_mov_b32_e32 v120, v127
	v_mov_b32_e32 v111, v127
	v_mov_b32_e32 v110, v127
	v_mov_b32_e32 v109, v127
	v_mov_b32_e32 v108, v127
	v_mov_b32_e32 v107, v127
	v_mov_b32_e32 v106, v127
	v_mov_b32_e32 v105, v127
	v_mov_b32_e32 v104, v127
	v_mov_b32_e32 v95, v127
	v_mov_b32_e32 v94, v127
	v_mov_b32_e32 v93, v127
	v_mov_b32_e32 v92, v127
	v_mov_b32_e32 v91, v127
	v_mov_b32_e32 v90, v127
	v_mov_b32_e32 v89, v127
	v_mov_b32_e32 v88, v127
	v_mov_b32_e32 v79, v127
	v_mov_b32_e32 v78, v127
	v_mov_b32_e32 v77, v127
	v_mov_b32_e32 v76, v127
	v_mov_b32_e32 v75, v127
	v_mov_b32_e32 v74, v127
	v_mov_b32_e32 v73, v127
	v_mov_b32_e32 v72, v127
	v_mov_b32_e32 v119, v127
	v_mov_b32_e32 v118, v127
	v_mov_b32_e32 v117, v127
	v_mov_b32_e32 v116, v127
	v_mov_b32_e32 v115, v127
	v_mov_b32_e32 v114, v127
	v_mov_b32_e32 v113, v127
	v_mov_b32_e32 v112, v127
	v_mov_b32_e32 v103, v127
	v_mov_b32_e32 v102, v127
	v_mov_b32_e32 v101, v127
	v_mov_b32_e32 v100, v127
	v_mov_b32_e32 v99, v127
	v_mov_b32_e32 v98, v127
	v_mov_b32_e32 v97, v127
	v_mov_b32_e32 v96, v127
	v_mov_b32_e32 v87, v127
	v_mov_b32_e32 v86, v127
	v_mov_b32_e32 v85, v127
	v_mov_b32_e32 v84, v127
	v_mov_b32_e32 v83, v127
	v_mov_b32_e32 v82, v127
	v_mov_b32_e32 v81, v127
	v_mov_b32_e32 v80, v127
	v_mov_b32_e32 v71, v127
	v_mov_b32_e32 v70, v127
	v_mov_b32_e32 v69, v127
	v_mov_b32_e32 v68, v127
	v_mov_b32_e32 v67, v127
	v_mov_b32_e32 v66, v127
	v_mov_b32_e32 v65, v127
	v_mov_b32_e32 v64, v127
	v_mov_b32_e32 v63, v127
	v_mov_b32_e32 v62, v127
	v_mov_b32_e32 v61, v127
	v_mov_b32_e32 v60, v127
	v_mov_b32_e32 v59, v127
	v_mov_b32_e32 v58, v127
	v_mov_b32_e32 v57, v127
	v_mov_b32_e32 v56, v127
	v_mov_b32_e32 v47, v127
	v_mov_b32_e32 v46, v127
	v_mov_b32_e32 v45, v127
	v_mov_b32_e32 v44, v127
	v_mov_b32_e32 v43, v127
	v_mov_b32_e32 v42, v127
	v_mov_b32_e32 v41, v127
	v_mov_b32_e32 v40, v127
	v_mov_b32_e32 v31, v127
	v_mov_b32_e32 v30, v127
	v_mov_b32_e32 v29, v127
	v_mov_b32_e32 v28, v127
	v_mov_b32_e32 v27, v127
	v_mov_b32_e32 v26, v127
	v_mov_b32_e32 v25, v127
	v_mov_b32_e32 v24, v127
	v_mov_b32_e32 v15, v127
	v_mov_b32_e32 v14, v127
	v_mov_b32_e32 v13, v127
	v_mov_b32_e32 v12, v127
	v_mov_b32_e32 v11, v127
	v_mov_b32_e32 v10, v127
	v_mov_b32_e32 v9, v127
	v_mov_b32_e32 v8, v127
	v_mov_b32_e32 v55, v127
	v_mov_b32_e32 v54, v127
	v_mov_b32_e32 v53, v127
	v_mov_b32_e32 v52, v127
	v_mov_b32_e32 v51, v127
	v_mov_b32_e32 v50, v127
	v_mov_b32_e32 v49, v127
	v_mov_b32_e32 v48, v127
	v_mov_b32_e32 v39, v127
	v_mov_b32_e32 v38, v127
	v_mov_b32_e32 v37, v127
	v_mov_b32_e32 v36, v127
	v_mov_b32_e32 v35, v127
	v_mov_b32_e32 v34, v127
	v_mov_b32_e32 v33, v127
	v_mov_b32_e32 v32, v127
	v_mov_b32_e32 v23, v127
	v_mov_b32_e32 v22, v127
	v_mov_b32_e32 v21, v127
	v_mov_b32_e32 v20, v127
	v_mov_b32_e32 v19, v127
	v_mov_b32_e32 v18, v127
	v_mov_b32_e32 v17, v127
	v_mov_b32_e32 v16, v127
	v_mov_b32_e32 v7, v127
	v_mov_b32_e32 v6, v127
	v_mov_b32_e32 v5, v127
	v_mov_b32_e32 v4, v127
	v_mov_b32_e32 v3, v127
	v_mov_b32_e32 v2, v127
	v_mov_b32_e32 v1, v127
	v_mov_b32_e32 v0, v127
	s_cbranch_vccnz .LBB0_492
	s_add_u32 s4, s4, 0x80
	s_addc_u32 s5, s5, 0
	s_add_u32 vcc_lo, s60, 0x100
	s_addc_u32 vcc_hi, s61, 0
	s_mov_b32 s60, 0
